# v56 + norm1 row loop: counted waits on the prefetched x row (per load) and the never-taken denormal rescue around v_rsq removed
# speedup vs baseline: 1.0025x; 1.0025x over previous
; __device__ __forceinline__ float wave_sum(float v) {
; #pragma unroll
;     for (int o = 1; o < 64; o <<= 1) v += __shfl_xor(v, o);
;     return v;
; }
.Lp1_keep:
.Lp1_join:
	s_waitcnt vmcnt(15)
	v_mov_b32_e32 v14, v104
	v_mov_b32_e32 v15, v105
	v_mov_b32_e32 v16, v106
	v_mov_b32_e32 v17, v107
	s_waitcnt vmcnt(14)
	v_mov_b32_e32 v18, v108
	v_mov_b32_e32 v19, v109
	v_mov_b32_e32 v20, v110
	v_mov_b32_e32 v21, v111
	s_waitcnt vmcnt(13)
	v_mov_b32_e32 v22, v112
	v_mov_b32_e32 v23, v113
	v_mov_b32_e32 v24, v114
	v_mov_b32_e32 v25, v115
	s_waitcnt vmcnt(12)
	v_mov_b32_e32 v26, v116
	v_mov_b32_e32 v27, v117
	v_mov_b32_e32 v28, v118
	v_mov_b32_e32 v29, v119
	s_mov_b32 s37, s23
	s_add_i32 s23, s23, s32
	s_add_i32 s36, s23, s32
	s_cmp_ge_i32 s36, s0
	s_cselect_b32 s36, s37, s36
	s_cmp_ge_i32 s23, s0
	s_cselect_b32 s40, 1, 0
	s_mov_b32 s34, s36
	s_cmpk_gt_i32 s34, 0x7fff
	s_cselect_b32 s20, s6, s4
	s_cselect_b32 s21, s7, s5
	s_cselect_b32 s8, 0x8000, 0
	s_sub_i32 s8, s34, s8
	s_lshl_b64 s[38:39], s[8:9], 12
	s_add_u32 s20, s20, s38
	s_addc_u32 s21, s21, s39
	v_lshl_add_u64 v[120:121], s[20:21], 0, v[4:5]
	global_load_dwordx4 v[104:107], v[120:121], off nt
	global_load_dwordx4 v[108:111], v[120:121], off offset:1024 nt
	global_load_dwordx4 v[112:115], v[120:121], off offset:3072 nt
	global_load_dwordx4 v[116:119], v[120:121], off offset:2048 nt
	s_lshl_b64 s[16:17], s[16:17], 11
	v_pk_mul_f32 v[58:59], v[16:17], v[16:17]
	v_pk_mul_f32 v[60:61], v[14:15], v[14:15]
	v_pk_mul_f32 v[62:63], v[20:21], v[20:21]
	v_pk_mul_f32 v[64:65], v[18:19], v[18:19]
	v_pk_mov_b32 v[70:71], v[60:61], v[58:59] op_sel:[1,0]
	v_mov_b32_e32 v61, v59
	v_pk_mov_b32 v[58:59], v[64:65], v[62:63] op_sel:[1,0]
	v_mov_b32_e32 v65, v63
	v_mul_f32_e32 v69, v23, v23
	v_mul_f32_e32 v66, v27, v27
	v_mul_f32_e32 v68, v29, v29
	v_pk_add_f32 v[60:61], v[70:71], v[60:61]
	v_pk_add_f32 v[58:59], v[58:59], v[64:65]
	v_mul_f32_e32 v13, v22, v22
	v_mul_f32_e32 v72, v24, v24
	v_mul_f32_e32 v73, v25, v25
	v_pk_fma_f32 v[62:63], v[26:27], v[26:27], v[66:67] op_sel_hi:[1,1,0]
	v_pk_fma_f32 v[66:67], v[28:29], v[28:29], v[68:69] op_sel_hi:[1,1,0]
	v_pk_add_f32 v[60:61], v[60:61], v[60:61] op_sel:[0,1] op_sel_hi:[1,0]
	v_pk_add_f32 v[58:59], v[58:59], v[58:59] op_sel:[0,1] op_sel_hi:[1,0]
	v_mov_b32_e32 v63, v72
	v_mov_b32_e32 v67, v73
	v_mov_b32_e32 v61, v13
	v_mov_b32_e32 v59, v69
	v_pk_add_f32 v[62:63], v[62:63], v[66:67]
	v_pk_add_f32 v[58:59], v[60:61], v[58:59]
	s_waitcnt vmcnt(15)
	v_pk_add_f32 v[76:77], v[32:33], 1.0 op_sel_hi:[1,0]
	v_pk_add_f32 v[58:59], v[58:59], v[62:63]
	v_pk_add_f32 v[74:75], v[30:31], 1.0 op_sel_hi:[1,0]
	v_add_f32_e32 v13, v58, v59
	s_nop 1
	v_add_f32_dpp v13, v13, v13 quad_perm:[1,0,3,2] row_mask:0xf bank_mask:0xf
	s_waitcnt vmcnt(14)
	v_pk_add_f32 v[122:123], v[36:37], 1.0 op_sel_hi:[1,0]
	v_pk_add_f32 v[78:79], v[34:35], 1.0 op_sel_hi:[1,0]
	s_nop 1
	v_add_f32_dpp v13, v13, v13 quad_perm:[2,3,0,1] row_mask:0xf bank_mask:0xf
	s_nop 1
	v_add_f32_dpp v13, v13, v13 row_half_mirror row_mask:0xf bank_mask:0xf
	s_nop 1
	v_add_f32_dpp v13, v13, v13 row_mirror row_mask:0xf bank_mask:0xf
	s_nop 1
	v_mov_b32_e32 v60, v13
	s_nop 1
	v_permlane16_swap_b32_e32 v13, v60
	s_nop 0
	v_add_f32_e32 v13, v13, v60
	s_nop 1
	v_mov_b32_e32 v60, v13
	s_nop 1
	v_permlane32_swap_b32_e32 v13, v60
	s_nop 0
	v_add_f32_e32 v13, v13, v60
	v_lshl_add_u64 v[58:59], v[0:1], 0, s[16:17]
	v_fmamk_f32 v13, v13, 0x3a800000, v12
	v_rsq_f32_e32 v60, v13
	s_nop 0
	v_pk_mul_f32 v[16:17], v[60:61], v[16:17] op_sel_hi:[0,1]
	v_pk_mul_f32 v[14:15], v[60:61], v[14:15] op_sel_hi:[0,1]
	v_pk_mul_f32 v[20:21], v[60:61], v[20:21] op_sel_hi:[0,1]
	v_pk_mul_f32 v[18:19], v[60:61], v[18:19] op_sel_hi:[0,1]
	s_waitcnt vmcnt(12)
	v_pk_mul_f32 v[14:15], v[42:43], v[14:15]
	v_pk_mul_f32 v[16:17], v[44:45], v[16:17]
	v_pk_mul_f32 v[18:19], v[38:39], v[18:19]
	v_pk_mul_f32 v[20:21], v[40:41], v[20:21]
	s_waitcnt vmcnt(10)
	v_pk_fma_f32 v[16:17], v[76:77], v[16:17], v[52:53]
	v_pk_fma_f32 v[14:15], v[74:75], v[14:15], v[50:51]
	v_pk_fma_f32 v[20:21], v[122:123], v[20:21], v[48:49]
	v_pk_fma_f32 v[18:19], v[78:79], v[18:19], v[46:47]
	v_cvt_pk_bf16_f32 v14, v14, v15
	v_cvt_pk_bf16_f32 v15, v16, v17
	v_cvt_pk_bf16_f32 v16, v18, v19
	v_cvt_pk_bf16_f32 v17, v20, v21
	global_store_dwordx2 v[58:59], v[14:15], off sc1
	global_store_dwordx2 v[58:59], v[16:17], off offset:512 sc1
	v_pk_mul_f32 v[28:29], v[60:61], v[28:29] op_sel_hi:[0,1]
	v_pk_mul_f32 v[26:27], v[60:61], v[26:27] op_sel_hi:[0,1]
	v_pk_mul_f32 v[24:25], v[60:61], v[24:25] op_sel_hi:[0,1]
	v_pk_mul_f32 v[22:23], v[60:61], v[22:23] op_sel_hi:[0,1]
	s_waitcnt vmcnt(11)
	v_pk_add_f32 v[16:17], v[82:83], 1.0 op_sel_hi:[1,0]
	v_pk_add_f32 v[14:15], v[80:81], 1.0 op_sel_hi:[1,0]
	s_waitcnt vmcnt(10)
	v_pk_mul_f32 v[18:19], v[84:85], v[26:27]
	v_pk_mul_f32 v[20:21], v[86:87], v[28:29]
	s_waitcnt vmcnt(9)
	v_pk_add_f32 v[26:27], v[90:91], 1.0 op_sel_hi:[1,0]
	v_pk_add_f32 v[28:29], v[88:89], 1.0 op_sel_hi:[1,0]
	s_waitcnt vmcnt(8)
	v_pk_mul_f32 v[22:23], v[92:93], v[22:23]
	v_pk_mul_f32 v[24:25], v[94:95], v[24:25]
	s_waitcnt vmcnt(7)
	v_pk_fma_f32 v[16:17], v[16:17], v[20:21], v[98:99]
	v_pk_fma_f32 v[14:15], v[14:15], v[18:19], v[96:97]
	s_waitcnt vmcnt(6)
	v_pk_fma_f32 v[18:19], v[26:27], v[24:25], v[102:103]
	v_pk_fma_f32 v[20:21], v[28:29], v[22:23], v[100:101]
	v_cvt_pk_bf16_f32 v14, v14, v15
	v_cvt_pk_bf16_f32 v15, v16, v17
	v_cvt_pk_bf16_f32 v16, v20, v21
	v_cvt_pk_bf16_f32 v17, v18, v19
	global_store_dwordx2 v[58:59], v[14:15], off offset:1024 sc1
	global_store_dwordx2 v[58:59], v[16:17], off offset:1536 sc1
	s_cmp_lg_u32 s40, 0
	s_cbranch_scc0 .Lp1_loopB
	s_branch .Lp1_exit

; __device__ __forceinline__ float wave_sum(float v) {
; #pragma unroll
;     for (int o = 1; o < 64; o <<= 1) v += __shfl_xor(v, o);
;     return v;
; }
.Lp1_keepB:
.Lp1_joinB:
	s_waitcnt vmcnt(15)
	v_mov_b32_e32 v14, v130
	v_mov_b32_e32 v15, v131
	v_mov_b32_e32 v16, v132
	v_mov_b32_e32 v17, v133
	s_waitcnt vmcnt(14)
	v_mov_b32_e32 v18, v134
	v_mov_b32_e32 v19, v135
	v_mov_b32_e32 v20, v136
	v_mov_b32_e32 v21, v137
	s_waitcnt vmcnt(13)
	v_mov_b32_e32 v22, v138
	v_mov_b32_e32 v23, v139
	v_mov_b32_e32 v24, v140
	v_mov_b32_e32 v25, v141
	s_waitcnt vmcnt(12)
	v_mov_b32_e32 v26, v142
	v_mov_b32_e32 v27, v143
	v_mov_b32_e32 v28, v144
	v_mov_b32_e32 v29, v145
	s_mov_b32 s37, s23
	s_add_i32 s23, s23, s32
	s_add_i32 s36, s23, s32
	s_cmp_ge_i32 s36, s0
	s_cselect_b32 s36, s37, s36
	s_cmp_ge_i32 s23, s0
	s_cselect_b32 s40, 1, 0
	s_mov_b32 s34, s36
	s_cmpk_gt_i32 s34, 0x7fff
	s_cselect_b32 s20, s6, s4
	s_cselect_b32 s21, s7, s5
	s_cselect_b32 s8, 0x8000, 0
	s_sub_i32 s8, s34, s8
	s_lshl_b64 s[38:39], s[8:9], 12
	s_add_u32 s20, s20, s38
	s_addc_u32 s21, s21, s39
	v_lshl_add_u64 v[120:121], s[20:21], 0, v[4:5]
	global_load_dwordx4 v[130:133], v[120:121], off nt
	global_load_dwordx4 v[134:137], v[120:121], off offset:1024 nt
	global_load_dwordx4 v[138:141], v[120:121], off offset:3072 nt
	global_load_dwordx4 v[142:145], v[120:121], off offset:2048 nt
	s_lshl_b64 s[16:17], s[16:17], 11
	v_pk_mul_f32 v[58:59], v[16:17], v[16:17]
	v_pk_mul_f32 v[60:61], v[14:15], v[14:15]
	v_pk_mul_f32 v[62:63], v[20:21], v[20:21]
	v_pk_mul_f32 v[64:65], v[18:19], v[18:19]
	v_pk_mov_b32 v[70:71], v[60:61], v[58:59] op_sel:[1,0]
	v_mov_b32_e32 v61, v59
	v_pk_mov_b32 v[58:59], v[64:65], v[62:63] op_sel:[1,0]
	v_mov_b32_e32 v65, v63
	v_mul_f32_e32 v69, v23, v23
	v_mul_f32_e32 v66, v27, v27
	v_mul_f32_e32 v68, v29, v29
	v_pk_add_f32 v[60:61], v[70:71], v[60:61]
	v_pk_add_f32 v[58:59], v[58:59], v[64:65]
	v_mul_f32_e32 v13, v22, v22
	v_mul_f32_e32 v72, v24, v24
	v_mul_f32_e32 v73, v25, v25
	v_pk_fma_f32 v[62:63], v[26:27], v[26:27], v[66:67] op_sel_hi:[1,1,0]
	v_pk_fma_f32 v[66:67], v[28:29], v[28:29], v[68:69] op_sel_hi:[1,1,0]
	v_pk_add_f32 v[60:61], v[60:61], v[60:61] op_sel:[0,1] op_sel_hi:[1,0]
	v_pk_add_f32 v[58:59], v[58:59], v[58:59] op_sel:[0,1] op_sel_hi:[1,0]
	v_mov_b32_e32 v63, v72
	v_mov_b32_e32 v67, v73
	v_mov_b32_e32 v61, v13
	v_mov_b32_e32 v59, v69
	v_pk_add_f32 v[62:63], v[62:63], v[66:67]
	v_pk_add_f32 v[58:59], v[60:61], v[58:59]
	s_waitcnt vmcnt(15)
	v_pk_add_f32 v[76:77], v[32:33], 1.0 op_sel_hi:[1,0]
	v_pk_add_f32 v[58:59], v[58:59], v[62:63]
	v_pk_add_f32 v[74:75], v[30:31], 1.0 op_sel_hi:[1,0]
	v_add_f32_e32 v13, v58, v59
	s_nop 1
	v_add_f32_dpp v13, v13, v13 quad_perm:[1,0,3,2] row_mask:0xf bank_mask:0xf
	s_waitcnt vmcnt(14)
	v_pk_add_f32 v[122:123], v[36:37], 1.0 op_sel_hi:[1,0]
	v_pk_add_f32 v[78:79], v[34:35], 1.0 op_sel_hi:[1,0]
	s_nop 1
	v_add_f32_dpp v13, v13, v13 quad_perm:[2,3,0,1] row_mask:0xf bank_mask:0xf
	s_nop 1
	v_add_f32_dpp v13, v13, v13 row_half_mirror row_mask:0xf bank_mask:0xf
	s_nop 1
	v_add_f32_dpp v13, v13, v13 row_mirror row_mask:0xf bank_mask:0xf
	s_nop 1
	v_mov_b32_e32 v60, v13
	s_nop 1
	v_permlane16_swap_b32_e32 v13, v60
	s_nop 0
	v_add_f32_e32 v13, v13, v60
	s_nop 1
	v_mov_b32_e32 v60, v13
	s_nop 1
	v_permlane32_swap_b32_e32 v13, v60
	s_nop 0
	v_add_f32_e32 v13, v13, v60
	v_lshl_add_u64 v[58:59], v[0:1], 0, s[16:17]
	v_fmamk_f32 v13, v13, 0x3a800000, v12
	v_rsq_f32_e32 v60, v13
	s_nop 0
	v_pk_mul_f32 v[16:17], v[60:61], v[16:17] op_sel_hi:[0,1]
	v_pk_mul_f32 v[14:15], v[60:61], v[14:15] op_sel_hi:[0,1]
	v_pk_mul_f32 v[20:21], v[60:61], v[20:21] op_sel_hi:[0,1]
	v_pk_mul_f32 v[18:19], v[60:61], v[18:19] op_sel_hi:[0,1]
	s_waitcnt vmcnt(12)
	v_pk_mul_f32 v[14:15], v[42:43], v[14:15]
	v_pk_mul_f32 v[16:17], v[44:45], v[16:17]
	v_pk_mul_f32 v[18:19], v[38:39], v[18:19]
	v_pk_mul_f32 v[20:21], v[40:41], v[20:21]
	s_waitcnt vmcnt(10)
	v_pk_fma_f32 v[16:17], v[76:77], v[16:17], v[52:53]
	v_pk_fma_f32 v[14:15], v[74:75], v[14:15], v[50:51]
	v_pk_fma_f32 v[20:21], v[122:123], v[20:21], v[48:49]
	v_pk_fma_f32 v[18:19], v[78:79], v[18:19], v[46:47]
	v_cvt_pk_bf16_f32 v14, v14, v15
	v_cvt_pk_bf16_f32 v15, v16, v17
	v_cvt_pk_bf16_f32 v16, v18, v19
	v_cvt_pk_bf16_f32 v17, v20, v21
	global_store_dwordx2 v[58:59], v[14:15], off sc1
	global_store_dwordx2 v[58:59], v[16:17], off offset:512 sc1
	v_pk_mul_f32 v[28:29], v[60:61], v[28:29] op_sel_hi:[0,1]
	v_pk_mul_f32 v[26:27], v[60:61], v[26:27] op_sel_hi:[0,1]
	v_pk_mul_f32 v[24:25], v[60:61], v[24:25] op_sel_hi:[0,1]
	v_pk_mul_f32 v[22:23], v[60:61], v[22:23] op_sel_hi:[0,1]
	s_waitcnt vmcnt(11)
	v_pk_add_f32 v[16:17], v[82:83], 1.0 op_sel_hi:[1,0]
	v_pk_add_f32 v[14:15], v[80:81], 1.0 op_sel_hi:[1,0]
	s_waitcnt vmcnt(10)
	v_pk_mul_f32 v[18:19], v[84:85], v[26:27]
	v_pk_mul_f32 v[20:21], v[86:87], v[28:29]
	s_waitcnt vmcnt(9)
	v_pk_add_f32 v[26:27], v[90:91], 1.0 op_sel_hi:[1,0]
	v_pk_add_f32 v[28:29], v[88:89], 1.0 op_sel_hi:[1,0]
	s_waitcnt vmcnt(8)
	v_pk_mul_f32 v[22:23], v[92:93], v[22:23]
	v_pk_mul_f32 v[24:25], v[94:95], v[24:25]
	s_waitcnt vmcnt(7)
	v_pk_fma_f32 v[16:17], v[16:17], v[20:21], v[98:99]
	v_pk_fma_f32 v[14:15], v[14:15], v[18:19], v[96:97]
	s_waitcnt vmcnt(6)
	v_pk_fma_f32 v[18:19], v[26:27], v[24:25], v[102:103]
	v_pk_fma_f32 v[20:21], v[28:29], v[22:23], v[100:101]
	v_cvt_pk_bf16_f32 v14, v14, v15
	v_cvt_pk_bf16_f32 v15, v16, v17
	v_cvt_pk_bf16_f32 v16, v20, v21
	v_cvt_pk_bf16_f32 v17, v18, v19
	global_store_dwordx2 v[58:59], v[14:15], off offset:1024 sc1
	global_store_dwordx2 v[58:59], v[16:17], off offset:1536 sc1
	s_cmp_lg_u32 s40, 0
	s_cbranch_scc0 .Lp1_loop
